# gemm_in: blocks 256..511 start their tile sequence 4 us later so the two blocks of a CU are not in their store-only epilogues at the same time
# baseline (speedup 1.0000x reference)
.LBB0_310:
	s_and_b64 vcc, exec, s[4:5]
	s_cbranch_vccz .LBB0_1088
	v_readlane_b32 s0, v255, 42
	s_cmp_gt_i32 s0, -1
	s_mov_b64 s[4:5], -1
	s_cbranch_scc0 .LBB0_1345
	v_readlane_b32 s0, v255, 42
	s_cmp_gt_i32 s0, 0
	s_cbranch_scc0 .LBB0_1090
	v_readlane_b32 s4, v254, 39
	v_readlane_b32 s5, v254, 40
	v_mov_b32_e32 v0, v171
	s_andn2_b64 vcc, exec, s[4:5]
	s_cbranch_vccnz .LBB0_1089
	v_readlane_b32 s4, v255, 43
	v_lshrrev_b32_e32 v1, 4, v0
	v_bfe_u32 v4, v0, 1, 3
	s_mul_hi_i32 s0, s4, 0x1880000
	s_mul_i32 s4, s4, 0x1880000
	v_xor_b32_e32 v2, v1, v0
	v_bitop3_b32 v1, v1, v4, 3 bitop3:0x6c
	v_lshlrev_b32_e32 v4, 4, v0
	s_add_u32 s12, s20, s4
	v_and_b32_e32 v4, 0x70, v4
	v_ashrrev_i32_e32 v5, 3, v0
	v_bfe_u32 v6, v0, 6, 1
	s_addc_u32 s13, s21, s0
	v_and_b32_e32 v166, 15, v0
	v_lshlrev_b32_e32 v2, 4, v2
	v_lshl_or_b32 v134, v5, 12, v4
	v_lshlrev_b32_e32 v4, 7, v5
	s_movk_i32 s0, 0x70
	v_lshlrev_b32_e32 v173, 6, v6
	v_bfe_u32 v3, v0, 4, 2
	v_and_or_b32 v167, v2, s0, v4
	v_or_b32_e32 v2, v173, v166
	v_and_b32_e32 v174, 0xffffff80, v0
	v_lshlrev_b32_e32 v0, 7, v0
	v_lshlrev_b32_e32 v2, 7, v2
	v_and_b32_e32 v0, 0xffffc780, v0
	v_lshlrev_b32_e32 v1, 4, v1
	v_or_b32_e32 v175, v2, v1
	v_or_b32_e32 v176, v0, v1
	v_bitop3_b32 v177, v2, v1, 64 bitop3:0xf6
	v_xor_b32_e32 v1, 64, v1
	v_lshlrev_b32_e32 v179, 2, v3
	v_or_b32_e32 v178, v0, v1
	v_lshl_or_b32 v0, v6, 5, v179
	v_mov_b32_e32 v135, v169
	v_add_u32_e32 v136, 0x20000, v134
	v_mov_b32_e32 v137, v169
	v_add_u32_e32 v138, 0x40000, v134
	v_mov_b32_e32 v139, v169
	v_add_u32_e32 v140, 0x60000, v134
	v_mov_b32_e32 v141, v169
	v_add_u32_e32 v142, 0x80000, v134
	v_mov_b32_e32 v143, v169
	v_add_u32_e32 v144, 0xa0000, v134
	v_mov_b32_e32 v145, v169
	v_add_u32_e32 v146, 0xc0000, v134
	v_mov_b32_e32 v147, v169
	v_add_u32_e32 v148, 0xe0000, v134
	v_mov_b32_e32 v149, v169
	s_mov_b32 s14, 0
	v_lshlrev_b32_e32 v180, 3, v0
	v_readlane_b32 s100, v255, 41
	s_nop 0
	s_and_b32 s100, s100, 0x100
	s_cmp_lg_u32 s100, 0x100
	s_cbranch_scc1 .Lgin_nodelay
	s_memrealtime s[100:101]
	s_waitcnt lgkmcnt(0)
	s_add_u32 s32, s100, 400
.Lgin_delay:
	s_sleep 4
	s_memrealtime s[100:101]
	s_waitcnt lgkmcnt(0)
	s_sub_u32 s100, s32, s100
	s_cmp_gt_i32 s100, 0
	s_cbranch_scc1 .Lgin_delay
.Lgin_nodelay:
	v_readlane_b32 s9, v254, 48
	v_readlane_b32 s5, v255, 44
	s_branch .LBB0_316

	.amdhsa_kernel _Z11mega_kernel6Params
		.amdhsa_group_segment_fixed_size 73744
		.amdhsa_private_segment_fixed_size 0
		.amdhsa_kernarg_size 496
		.amdhsa_user_sgpr_count 2
		.amdhsa_user_sgpr_dispatch_ptr 0
		.amdhsa_user_sgpr_queue_ptr 0
		.amdhsa_user_sgpr_kernarg_segment_ptr 1
		.amdhsa_user_sgpr_dispatch_id 0
		.amdhsa_user_sgpr_kernarg_preload_length 0
		.amdhsa_user_sgpr_kernarg_preload_offset 0
		.amdhsa_user_sgpr_private_segment_size 0
		.amdhsa_uses_dynamic_stack 0
		.amdhsa_enable_private_segment 0
		.amdhsa_system_sgpr_workgroup_id_x 1
		.amdhsa_system_sgpr_workgroup_id_y 0
		.amdhsa_system_sgpr_workgroup_id_z 0
		.amdhsa_system_sgpr_workgroup_info 0
		.amdhsa_system_vgpr_workitem_id 2
		.amdhsa_next_free_vgpr 256
		.amdhsa_next_free_sgpr 102
		.amdhsa_accum_offset 256
		.amdhsa_reserve_vcc 1
		.amdhsa_float_round_mode_32 0
		.amdhsa_float_round_mode_16_64 0
		.amdhsa_float_denorm_mode_32 3
		.amdhsa_float_denorm_mode_16_64 3
		.amdhsa_dx10_clamp 1
		.amdhsa_ieee_mode 1
		.amdhsa_fp16_overflow 0
		.amdhsa_tg_split 0
		.amdhsa_exception_fp_ieee_invalid_op 0
		.amdhsa_exception_fp_denorm_src 0
		.amdhsa_exception_fp_ieee_div_zero 0
		.amdhsa_exception_fp_ieee_overflow 0
		.amdhsa_exception_fp_ieee_underflow 0
		.amdhsa_exception_fp_ieee_inexact 0
		.amdhsa_exception_int_div_zero 0
	.end_amdhsa_kernel

amdhsa.kernels:
  - .agpr_count:     0
    .args:
      - .offset:         0
        .size:           240
        .value_kind:     by_value
      - .offset:         240
        .size:           4
        .value_kind:     hidden_block_count_x
      - .offset:         244
        .size:           4
        .value_kind:     hidden_block_count_y
      - .offset:         248
        .size:           4
        .value_kind:     hidden_block_count_z
      - .offset:         252
        .size:           2
        .value_kind:     hidden_group_size_x
      - .offset:         254
        .size:           2
        .value_kind:     hidden_group_size_y
      - .offset:         256
        .size:           2
        .value_kind:     hidden_group_size_z
      - .offset:         258
        .size:           2
        .value_kind:     hidden_remainder_x
      - .offset:         260
        .size:           2
        .value_kind:     hidden_remainder_y
      - .offset:         262
        .size:           2
        .value_kind:     hidden_remainder_z
      - .offset:         280
        .size:           8
        .value_kind:     hidden_global_offset_x
      - .offset:         288
        .size:           8
        .value_kind:     hidden_global_offset_y
      - .offset:         296
        .size:           8
        .value_kind:     hidden_global_offset_z
      - .offset:         304
        .size:           2
        .value_kind:     hidden_grid_dims
      - .offset:         328
        .size:           8
        .value_kind:     hidden_multigrid_sync_arg
    .group_segment_fixed_size: 73744
    .kernarg_segment_align: 8
    .kernarg_segment_size: 496
    .language:       OpenCL C
    .language_version:
      - 2
      - 0
    .max_flat_workgroup_size: 256
    .name:           _Z11mega_kernel6Params
    .private_segment_fixed_size: 0
    .sgpr_count:     108
    .sgpr_spill_count: 207
    .symbol:         _Z11mega_kernel6Params.kd
    .uniform_work_group_size: 1
    .uses_dynamic_stack: false
    .vgpr_count:     256
    .vgpr_spill_count: 0
    .wavefront_size: 64
